# MLA variant 5: nine K fragment reads up front (first two in not-yet-written score registers)
# speedup vs baseline: 1.0045x; 1.0004x over previous
.LBB0_190:
	s_bitcmp1_b32 s1, 0
	s_cselect_b32 s0, 0x7000, 0
	v_add_u32_e32 v100, s0, v174
	v_add3_u32 v185, s0, v192, v159
	v_add3_u32 v100, v100, v175, v176
	v_add_u32_e32 v184, v100, v177
	v_add_u32_e32 v183, v100, v178
	v_add_u32_e32 v182, v100, v179
	v_add_u32_e32 v181, v100, v180
	ds_read_b64_tr_b16 v[112:113], v184 offset:20480
	ds_read_b64_tr_b16 v[114:115], v184 offset:20992
	ds_read_b64_tr_b16 v[108:109], v183 offset:20480
	ds_read_b64_tr_b16 v[110:111], v183 offset:20992
	ds_read_b64_tr_b16 v[104:105], v182 offset:20480
	ds_read_b64_tr_b16 v[106:107], v182 offset:20992
	ds_read_b64_tr_b16 v[100:101], v181 offset:20480
	ds_read_b64_tr_b16 v[102:103], v181 offset:20992
	ds_read_b128 v[132:135], v185
	ds_read_b128 v[116:119], v185 offset:64
	ds_read_b128 v[186:189], v185 offset:128
	ds_read_b128 v[144:147], v185 offset:1280
	ds_read_b128 v[128:131], v185 offset:1344
	ds_read_b128 v[140:143], v185 offset:1408
	ds_read_b128 v[124:127], v185 offset:10240
	ds_read_b128 v[194:197], v185 offset:10304
	ds_read_b128 v[202:205], v185 offset:10368
	s_waitcnt lgkmcnt(8)
	v_mfma_f32_16x16x32_bf16 v[136:139], v[132:135], v[12:15], v[36:39]
	v_mfma_f32_16x16x32_bf16 v[120:123], v[132:135], v[20:23], v[48:51]
	s_waitcnt lgkmcnt(7)
	v_mfma_f32_16x16x32_bf16 v[136:139], v[116:119], v[16:19], v[136:139]
	v_mfma_f32_16x16x32_bf16 v[120:123], v[116:119], v[24:27], v[120:123]
	s_waitcnt lgkmcnt(6)
	v_mfma_f32_16x16x32_bf16 v[136:139], v[186:189], v[0:3], v[136:139]
	v_mfma_f32_16x16x32_bf16 v[120:123], v[186:189], v[4:7], v[120:123]
	ds_read_b128 v[186:189], v185 offset:11520
	s_andn2_b32 s0, 1, s1
	s_mulk_i32 s0, 0x7000
	s_add_i32 s10, s1, 1
	v_add3_u32 v132, s0, v151, v155
	v_add3_u32 v133, s0, v157, v170
	v_add_u32_e32 v134, s0, v171
	s_waitcnt vmcnt(2)
	ds_write_b128 v132, v[8:11]
	v_add3_u32 v134, v134, v173, v172
	s_add_i32 s0, s1, 3
	s_min_u32 s0, s0, s83
	s_waitcnt vmcnt(0)
	ds_write_b128 v133, v[28:31]
	s_lshl_b32 s0, s0, 6
	ds_write_b128 v134, v[32:35] offset:20480
	v_add_u32_e32 v8, s0, v154
	v_add_u32_e32 v28, s0, v156
	s_add_i32 s0, s1, 2
	v_ashrrev_i32_e32 v9, 31, v8
	v_ashrrev_i32_e32 v29, 31, v28
	s_min_u32 s0, s0, s83
	v_lshlrev_b64 v[10:11], 11, v[8:9]
	v_lshlrev_b64 v[8:9], 6, v[8:9]
	v_lshlrev_b64 v[30:31], 11, v[28:29]
	v_lshlrev_b64 v[28:29], 6, v[28:29]
	v_lshl_add_u32 v32, s0, 6, v158
	v_lshl_add_u64 v[8:9], v[162:163], 0, v[8:9]
	v_lshl_add_u64 v[28:29], v[166:167], 0, v[28:29]
	v_ashrrev_i32_e32 v33, 31, v32
	v_lshl_add_u64 v[10:11], v[164:165], 0, v[10:11]
	v_lshl_add_u64 v[8:9], v[8:9], 0, s[58:59]
	v_lshl_add_u64 v[30:31], v[168:169], 0, v[30:31]
	v_lshl_add_u64 v[28:29], v[28:29], 0, s[58:59]
	v_lshlrev_b64 v[32:33], 11, v[32:33]
	v_cndmask_b32_e64 v9, v9, v11, s[6:7]
	v_cndmask_b32_e64 v8, v8, v10, s[6:7]
	v_cndmask_b32_e64 v29, v29, v31, s[8:9]
	v_cndmask_b32_e64 v28, v28, v30, s[8:9]
	v_lshl_add_u64 v[32:33], v[160:161], 0, v[32:33]
	global_load_dwordx4 v[8:11], v[8:9], off
	global_load_dwordx4 v[28:31], v[28:29], off
	global_load_dwordx4 v[32:35], v[32:33], off offset:128
	s_waitcnt lgkmcnt(9)
	v_mfma_f32_16x16x32_bf16 v[132:135], v[144:147], v[12:15], v[36:39]
	v_mfma_f32_16x16x32_bf16 v[116:119], v[144:147], v[20:23], v[48:51]
	s_waitcnt lgkmcnt(8)
	v_mfma_f32_16x16x32_bf16 v[132:135], v[128:131], v[16:19], v[132:135]
	v_mfma_f32_16x16x32_bf16 v[116:119], v[128:131], v[24:27], v[116:119]
	s_waitcnt lgkmcnt(7)
	v_mfma_f32_16x16x32_bf16 v[132:135], v[140:143], v[0:3], v[132:135]
	v_mfma_f32_16x16x32_bf16 v[116:119], v[140:143], v[4:7], v[116:119]
	s_waitcnt lgkmcnt(6)
	v_mfma_f32_16x16x32_bf16 v[140:143], v[124:127], v[12:15], v[36:39]
	v_mfma_f32_16x16x32_bf16 v[124:127], v[124:127], v[20:23], v[48:51]
	s_waitcnt lgkmcnt(5)
	v_mfma_f32_16x16x32_bf16 v[140:143], v[194:197], v[16:19], v[140:143]
	v_mfma_f32_16x16x32_bf16 v[124:127], v[194:197], v[24:27], v[124:127]
	ds_read_b128 v[194:197], v185 offset:11584
	s_waitcnt lgkmcnt(5)
	v_mfma_f32_16x16x32_bf16 v[140:143], v[202:205], v[0:3], v[140:143]
	v_mfma_f32_16x16x32_bf16 v[124:127], v[202:205], v[4:7], v[124:127]
	ds_read_b128 v[202:205], v185 offset:11648
	s_waitcnt lgkmcnt(5)
	v_mfma_f32_16x16x32_bf16 v[144:147], v[186:189], v[12:15], v[36:39]
	v_mfma_f32_16x16x32_bf16 v[128:131], v[186:189], v[20:23], v[48:51]
	s_waitcnt lgkmcnt(1)
	v_mfma_f32_16x16x32_bf16 v[144:147], v[194:197], v[16:19], v[144:147]
	v_mfma_f32_16x16x32_bf16 v[128:131], v[194:197], v[24:27], v[128:131]
	s_waitcnt lgkmcnt(0)
	v_mfma_f32_16x16x32_bf16 v[144:147], v[202:205], v[0:3], v[144:147]
	v_mfma_f32_16x16x32_bf16 v[128:131], v[202:205], v[4:7], v[128:131]
	s_cmp_ge_u32 s10, s82
	s_cbranch_scc1 .LBB0_196
	s_cmp_lg_u32 s1, 0
	s_cselect_b64 s[0:1], -1, 0
	s_and_b32 s11, s10, 3
	s_cmp_lg_u32 s11, 0
	s_cselect_b64 s[14:15], -1, 0
	s_and_b64 s[0:1], s[0:1], s[14:15]
	s_and_b64 vcc, exec, s[0:1]
	s_cbranch_vccnz .LBB0_196
	v_max_f32_e32 v185, v137, v137
	v_max_f32_e32 v186, v136, v136
	v_max_f32_e32 v185, v186, v185
	v_max3_f32 v185, v185, v138, v139
	v_max3_f32 v185, v185, v132, v133
	v_max3_f32 v185, v185, v134, v135
	v_max3_f32 v185, v185, v140, v141
	v_max3_f32 v185, v185, v142, v143
	v_max3_f32 v185, v185, v144, v145
	v_max3_f32 v185, v185, v146, v147
	v_mov_b32_e32 v186, v185
	s_nop 1
	v_permlane16_swap_b32_e32 v185, v186
	v_max_f32_e32 v186, v186, v186
	v_max_f32_e32 v185, v185, v185
	v_max_f32_e32 v185, v185, v186
	v_mov_b32_e32 v186, v185
	s_nop 1
	v_permlane32_swap_b32_e32 v185, v186
	v_max_f32_e32 v186, v186, v186
	v_max_f32_e32 v185, v185, v185
	v_max_f32_e32 v185, v185, v186
	v_cmp_lt_f32_e32 vcc, s44, v185
	s_cbranch_vccz .LBB0_194
	s_nop 0
	v_cndmask_b32_e32 v185, 0, v185, vcc
	v_exp_f32_e64 v186, -v185
	v_lshlrev_b32_e32 v188, 16, v56
	v_and_b32_e32 v189, 0xffff0000, v56
	v_sub_f32_e32 v139, v139, v185
	v_pk_mul_f32 v[188:189], v[186:187], v[188:189] op_sel_hi:[0,1]
	v_cvt_pk_bf16_f32 v56, v188, v189
	v_lshlrev_b32_e32 v188, 16, v57
	v_and_b32_e32 v189, 0xffff0000, v57
	v_pk_mul_f32 v[188:189], v[186:187], v[188:189] op_sel_hi:[0,1]
	v_cvt_pk_bf16_f32 v57, v188, v189
	v_lshlrev_b32_e32 v188, 16, v58
	v_and_b32_e32 v189, 0xffff0000, v58
	v_pk_mul_f32 v[188:189], v[186:187], v[188:189] op_sel_hi:[0,1]
	v_cvt_pk_bf16_f32 v58, v188, v189
	v_lshlrev_b32_e32 v188, 16, v59
	v_and_b32_e32 v189, 0xffff0000, v59
	v_pk_mul_f32 v[188:189], v[186:187], v[188:189] op_sel_hi:[0,1]
	v_cvt_pk_bf16_f32 v59, v188, v189
	v_lshlrev_b32_e32 v188, 16, v52
	v_and_b32_e32 v189, 0xffff0000, v52
	v_pk_mul_f32 v[188:189], v[186:187], v[188:189] op_sel_hi:[0,1]
	v_cvt_pk_bf16_f32 v52, v188, v189
	v_lshlrev_b32_e32 v188, 16, v53
	v_and_b32_e32 v189, 0xffff0000, v53
	v_pk_mul_f32 v[188:189], v[186:187], v[188:189] op_sel_hi:[0,1]
	v_cvt_pk_bf16_f32 v53, v188, v189
	v_lshlrev_b32_e32 v188, 16, v54
	v_and_b32_e32 v189, 0xffff0000, v54
	v_pk_mul_f32 v[188:189], v[186:187], v[188:189] op_sel_hi:[0,1]
	v_cvt_pk_bf16_f32 v54, v188, v189
	v_lshlrev_b32_e32 v188, 16, v55
	v_and_b32_e32 v189, 0xffff0000, v55
	v_pk_mul_f32 v[78:79], v[78:79], v[186:187] op_sel_hi:[1,0]
	v_pk_mul_f32 v[76:77], v[76:77], v[186:187] op_sel_hi:[1,0]
	v_pk_mul_f32 v[98:99], v[98:99], v[186:187] op_sel_hi:[1,0]
	v_pk_mul_f32 v[96:97], v[96:97], v[186:187] op_sel_hi:[1,0]
	v_pk_mul_f32 v[94:95], v[94:95], v[186:187] op_sel_hi:[1,0]
	v_pk_mul_f32 v[92:93], v[92:93], v[186:187] op_sel_hi:[1,0]
	v_pk_mul_f32 v[86:87], v[86:87], v[186:187] op_sel_hi:[1,0]
	v_pk_mul_f32 v[84:85], v[84:85], v[186:187] op_sel_hi:[1,0]
	v_pk_mul_f32 v[42:43], v[42:43], v[186:187] op_sel_hi:[1,0]
	v_pk_mul_f32 v[40:41], v[40:41], v[186:187] op_sel_hi:[1,0]
	v_pk_mul_f32 v[186:187], v[186:187], v[188:189] op_sel_hi:[0,1]
	v_sub_f32_e32 v138, v138, v185
	v_sub_f32_e32 v137, v137, v185
	v_sub_f32_e32 v136, v136, v185
	v_sub_f32_e32 v135, v135, v185
	v_sub_f32_e32 v134, v134, v185
	v_sub_f32_e32 v133, v133, v185
	v_sub_f32_e32 v132, v132, v185
	v_sub_f32_e32 v143, v143, v185
	v_sub_f32_e32 v142, v142, v185
	v_sub_f32_e32 v141, v141, v185
	v_sub_f32_e32 v140, v140, v185
	v_sub_f32_e32 v147, v147, v185
	v_sub_f32_e32 v146, v146, v185
	v_sub_f32_e32 v145, v145, v185
	v_sub_f32_e32 v144, v144, v185
	v_cvt_pk_bf16_f32 v55, v186, v187
	v_sub_f32_e32 v39, v39, v185
	v_sub_f32_e32 v38, v38, v185
	v_sub_f32_e32 v37, v37, v185
	v_sub_f32_e32 v36, v36, v185
